# grid barrier step 2: all workgroups poll the top arrival counter (released at (gen+1)*nXCD); generation word and its publishing add removed
# baseline (speedup 1.0000x reference)
.LBB0_107:
	s_or_b64 exec, exec, s[8:9]
	v_cvt_f32_u32_e32 v4, v2
	s_waitcnt vmcnt(0)
	v_readfirstlane_b32 s2, v3
	v_sub_u32_e32 v3, 0, v2
	v_rcp_iflag_f32_e32 v4, v4
	v_add_u32_e32 v5, s2, v1
	v_mul_f32_e32 v4, 0x4f7ffffe, v4
	v_cvt_u32_f32_e32 v4, v4
	v_mul_lo_u32 v1, v3, v4
	v_mul_hi_u32 v1, v4, v1
	v_add_u32_e32 v1, v4, v1
	v_mul_hi_u32 v1, v5, v1
	v_mul_lo_u32 v3, v1, v2
	v_sub_u32_e32 v3, v5, v3
	v_add_u32_e32 v4, 1, v1
	v_cmp_ge_u32_e32 vcc, v3, v2
	s_nop 1
	v_cndmask_b32_e32 v1, v1, v4, vcc
	v_sub_u32_e32 v4, v3, v2
	v_cndmask_b32_e32 v3, v3, v4, vcc
	v_add_u32_e32 v4, 1, v1
	v_cmp_ge_u32_e32 vcc, v3, v2
	v_add_u32_e32 v3, 1, v5
	s_nop 0
	v_cndmask_b32_e32 v1, v1, v4, vcc
	v_mul_lo_u32 v4, v2, v1
	v_add_u32_e32 v2, v4, v2
	v_cmp_ne_u32_e32 vcc, v3, v2
	s_and_saveexec_b64 s[2:3], vcc
	s_xor_b64 s[6:7], exec, s[2:3]
	s_cbranch_execz .LBB0_121
	s_waitcnt lgkmcnt(0)
	v_mad_u32_u24 v1, v1, v0, v0
	v_mov_b32_e32 v0, 0x3000
	global_load_dword v0, v0, s[36:37] offset:1024 sc1
	s_add_u32 s10, s36, 0x3400
	s_addc_u32 s11, s37, 0
	s_waitcnt vmcnt(0)
	v_cmp_lt_u32_e32 vcc, v0, v1
	s_and_saveexec_b64 s[8:9], vcc
	s_cbranch_execz .LBB0_120
	s_mov_b32 s2, 1
	s_mov_b64 s[12:13], 0
	v_mov_b32_e32 v0, 0
	s_branch .LBB0_111

.LBB0_113:
	global_load_dword v2, v0, s[10:11] sc1
	s_add_i32 s2, s2, 1
	s_mov_b64 s[18:19], -1
	s_waitcnt vmcnt(0)
	v_cmp_ge_u32_e32 vcc, v2, v1
	s_orn2_b64 s[16:17], vcc, exec
	s_branch .LBB0_110

.LBB0_124:
	s_or_b64 exec, exec, s[8:9]
	v_cvt_f32_u32_e32 v3, v0
	s_waitcnt vmcnt(0)
	v_readfirstlane_b32 s2, v2
	s_add_u32 s8, s36, 0x3400
	s_addc_u32 s9, s37, 0
	v_rcp_iflag_f32_e32 v3, v3
	v_add_u32_e32 v1, s2, v1
	v_add_u32_e32 v4, 1, v1
	s_mov_b64 s[10:11], -1
	v_mul_f32_e32 v2, 0x4f7ffffe, v3
	v_cvt_u32_f32_e32 v2, v2
	v_sub_u32_e32 v3, 0, v0
	v_mul_lo_u32 v3, v3, v2
	v_mul_hi_u32 v3, v2, v3
	v_add_u32_e32 v2, v2, v3
	v_mul_hi_u32 v2, v1, v2
	v_mul_lo_u32 v3, v2, v0
	v_sub_u32_e32 v1, v1, v3
	v_add_u32_e32 v5, 1, v2
	v_cmp_ge_u32_e32 vcc, v1, v0
	v_sub_u32_e32 v3, v1, v0
	s_nop 0
	v_cndmask_b32_e32 v2, v2, v5, vcc
	v_cndmask_b32_e32 v1, v1, v3, vcc
	v_add_u32_e32 v3, 1, v2
	v_cmp_ge_u32_e32 vcc, v1, v0
	s_nop 1
	v_cndmask_b32_e32 v2, v2, v3, vcc
	v_mul_lo_u32 v1, v0, v2
	v_add_u32_e32 v0, v1, v0
	v_mov_b32_e32 v7, v0
	v_cmp_ne_u32_e32 vcc, v4, v0
	v_mov_b64_e32 v[0:1], s[8:9]
	s_and_saveexec_b64 s[6:7], vcc
	s_cbranch_execz .LBB0_136
	v_mov_b32_e32 v0, 0
	global_load_dword v1, v0, s[8:9] sc1
	s_mov_b64 s[14:15], 0
	s_waitcnt vmcnt(0)
	v_cmp_lt_u32_e32 vcc, v1, v7
	s_and_saveexec_b64 s[12:13], vcc
	s_cbranch_execz .LBB0_135
	s_add_u32 s10, s36, 0x200
	s_addc_u32 s11, s37, 0
	s_mov_b32 s2, 1
	s_branch .LBB0_128

.LBB0_130:
	global_load_dword v1, v0, s[8:9] sc1
	s_add_i32 s2, s2, 1
	s_mov_b64 s[18:19], -1
	s_waitcnt vmcnt(0)
	v_cmp_ge_u32_e32 vcc, v1, v7
	s_orn2_b64 s[22:23], vcc, exec
	s_branch .LBB0_127

.LBB0_136:
	s_or_b64 exec, exec, s[6:7]
	s_and_saveexec_b64 s[6:7], s[10:11]
	s_cbranch_execz .LBB0_138
.LBB0_138:
	s_or_b64 exec, exec, s[6:7]
	s_mov_b64 s[6:7], exec
	v_mbcnt_lo_u32_b32 v0, s6, 0
	v_mbcnt_hi_u32_b32 v0, s7, v0
	v_cmp_eq_u32_e32 vcc, 0, v0
	s_waitcnt vmcnt(0)
	buffer_inv sc1
	s_and_saveexec_b64 s[8:9], vcc
	s_cbranch_execz .LBB0_140
	s_bcnt1_i32_b64 s2, s[6:7]

.LBB0_342:
	s_or_b64 exec, exec, s[8:9]
	v_cvt_f32_u32_e32 v4, v2
	s_waitcnt vmcnt(0)
	v_readfirstlane_b32 s2, v3
	v_sub_u32_e32 v3, 0, v2
	v_rcp_iflag_f32_e32 v4, v4
	v_add_u32_e32 v5, s2, v1
	v_mul_f32_e32 v4, 0x4f7ffffe, v4
	v_cvt_u32_f32_e32 v4, v4
	v_mul_lo_u32 v1, v3, v4
	v_mul_hi_u32 v1, v4, v1
	v_add_u32_e32 v1, v4, v1
	v_mul_hi_u32 v1, v5, v1
	v_mul_lo_u32 v3, v1, v2
	v_sub_u32_e32 v3, v5, v3
	v_add_u32_e32 v4, 1, v1
	v_cmp_ge_u32_e32 vcc, v3, v2
	s_nop 1
	v_cndmask_b32_e32 v1, v1, v4, vcc
	v_sub_u32_e32 v4, v3, v2
	v_cndmask_b32_e32 v3, v3, v4, vcc
	v_add_u32_e32 v4, 1, v1
	v_cmp_ge_u32_e32 vcc, v3, v2
	v_add_u32_e32 v3, 1, v5
	s_nop 0
	v_cndmask_b32_e32 v1, v1, v4, vcc
	v_mul_lo_u32 v4, v2, v1
	v_add_u32_e32 v2, v4, v2
	v_cmp_ne_u32_e32 vcc, v3, v2
	s_and_saveexec_b64 s[6:7], vcc
	s_xor_b64 s[6:7], exec, s[6:7]
	s_cbranch_execz .LBB0_356
	s_waitcnt lgkmcnt(0)
	v_mad_u32_u24 v1, v1, v0, v0
	v_mov_b32_e32 v0, 0x3000
	global_load_dword v0, v0, s[36:37] offset:1024 sc1
	s_add_u32 s10, s36, 0x3400
	s_addc_u32 s11, s37, 0
	s_waitcnt vmcnt(0)
	v_cmp_lt_u32_e32 vcc, v0, v1
	s_and_saveexec_b64 s[8:9], vcc
	s_cbranch_execz .LBB0_355
	s_mov_b32 s2, 1
	s_mov_b64 s[12:13], 0
	v_mov_b32_e32 v0, 0
	s_branch .LBB0_346

.LBB0_371:
	s_or_b64 exec, exec, s[6:7]
	s_and_saveexec_b64 s[6:7], s[10:11]
	s_cbranch_execz .LBB0_373
.LBB0_373:
	s_or_b64 exec, exec, s[6:7]
	s_mov_b64 s[6:7], exec
	v_mbcnt_lo_u32_b32 v0, s6, 0
	v_mbcnt_hi_u32_b32 v0, s7, v0
	v_cmp_eq_u32_e32 vcc, 0, v0
	s_waitcnt vmcnt(0)
	buffer_inv sc1
	s_and_saveexec_b64 s[8:9], vcc
	s_cbranch_execz .LBB0_375
	s_bcnt1_i32_b64 s2, s[6:7]

.LBB0_483:
	s_or_b64 exec, exec, s[6:7]
	s_and_saveexec_b64 s[6:7], s[10:11]
	s_cbranch_execz .LBB0_485
.LBB0_485:
	s_or_b64 exec, exec, s[6:7]
	s_mov_b64 s[6:7], exec
	v_mbcnt_lo_u32_b32 v0, s6, 0
	v_mbcnt_hi_u32_b32 v0, s7, v0
	v_cmp_eq_u32_e32 vcc, 0, v0
	s_waitcnt vmcnt(0)
	buffer_inv sc1
	s_and_saveexec_b64 s[8:9], vcc
	s_cbranch_execz .LBB0_487
	s_bcnt1_i32_b64 s2, s[6:7]

.LBB0_561:
	s_or_b64 exec, exec, s[6:7]
	s_and_saveexec_b64 s[6:7], s[10:11]
	s_cbranch_execz .LBB0_563
.LBB0_563:
	s_or_b64 exec, exec, s[6:7]
	s_mov_b64 s[6:7], exec
	v_mbcnt_lo_u32_b32 v0, s6, 0
	v_mbcnt_hi_u32_b32 v0, s7, v0
	v_cmp_eq_u32_e32 vcc, 0, v0
	s_waitcnt vmcnt(0)
	buffer_inv sc1
	s_and_saveexec_b64 s[8:9], vcc
	s_cbranch_execz .LBB0_565
	s_bcnt1_i32_b64 s2, s[6:7]

.LBB0_624:
	s_or_b64 exec, exec, s[6:7]
	s_and_saveexec_b64 s[6:7], s[10:11]
	s_cbranch_execz .LBB0_626
.LBB0_626:
	s_or_b64 exec, exec, s[6:7]
	s_mov_b64 s[6:7], exec
	v_mbcnt_lo_u32_b32 v0, s6, 0
	v_mbcnt_hi_u32_b32 v0, s7, v0
	v_cmp_eq_u32_e32 vcc, 0, v0
	s_waitcnt vmcnt(0)
	buffer_inv sc1
	s_and_saveexec_b64 s[8:9], vcc
	s_cbranch_execz .LBB0_628
	s_bcnt1_i32_b64 s2, s[6:7]

.LBB0_679:
	s_or_b64 exec, exec, s[6:7]
	s_and_saveexec_b64 s[6:7], s[10:11]
	s_cbranch_execz .LBB0_681
.LBB0_681:
	s_or_b64 exec, exec, s[6:7]
	s_mov_b64 s[6:7], exec
	v_mbcnt_lo_u32_b32 v0, s6, 0
	v_mbcnt_hi_u32_b32 v0, s7, v0
	v_cmp_eq_u32_e32 vcc, 0, v0
	s_waitcnt vmcnt(0)
	buffer_inv sc1
	s_and_saveexec_b64 s[8:9], vcc
	s_cbranch_execz .LBB0_683
	s_bcnt1_i32_b64 s2, s[6:7]

.LBB0_742:
	s_or_b64 exec, exec, s[6:7]
	s_and_saveexec_b64 s[6:7], s[10:11]
	s_cbranch_execz .LBB0_744
.LBB0_744:
	s_or_b64 exec, exec, s[6:7]
	s_mov_b64 s[6:7], exec
	v_mbcnt_lo_u32_b32 v0, s6, 0
	v_mbcnt_hi_u32_b32 v0, s7, v0
	v_cmp_eq_u32_e32 vcc, 0, v0
	s_waitcnt vmcnt(0)
	buffer_inv sc1
	s_and_saveexec_b64 s[8:9], vcc
	s_cbranch_execz .LBB0_746
	s_bcnt1_i32_b64 s2, s[6:7]

.LBB0_805:
	s_or_b64 exec, exec, s[6:7]
	s_and_saveexec_b64 s[6:7], s[10:11]
	s_cbranch_execz .LBB0_807
.LBB0_807:
	s_or_b64 exec, exec, s[6:7]
	s_mov_b64 s[6:7], exec
	v_mbcnt_lo_u32_b32 v0, s6, 0
	v_mbcnt_hi_u32_b32 v0, s7, v0
	v_cmp_eq_u32_e32 vcc, 0, v0
	s_waitcnt vmcnt(0)
	buffer_inv sc1
	s_and_saveexec_b64 s[8:9], vcc
	s_cbranch_execz .LBB0_809
	s_bcnt1_i32_b64 s2, s[6:7]

.LBB0_860:
	s_or_b64 exec, exec, s[6:7]
	s_and_saveexec_b64 s[6:7], s[10:11]
	s_cbranch_execz .LBB0_862
.LBB0_862:
	s_or_b64 exec, exec, s[6:7]
	s_mov_b64 s[6:7], exec
	v_mbcnt_lo_u32_b32 v0, s6, 0
	v_mbcnt_hi_u32_b32 v0, s7, v0
	v_cmp_eq_u32_e32 vcc, 0, v0
	s_waitcnt vmcnt(0)
	buffer_inv sc1
	s_and_saveexec_b64 s[8:9], vcc
	s_cbranch_execz .LBB0_864
	s_bcnt1_i32_b64 s2, s[6:7]

.LBB0_1576:
	s_or_b64 exec, exec, s[6:7]
	s_and_saveexec_b64 s[6:7], s[10:11]
	s_cbranch_execz .LBB0_1578
.LBB0_1578:
	s_or_b64 exec, exec, s[6:7]
	s_mov_b64 s[6:7], exec
	v_mbcnt_lo_u32_b32 v0, s6, 0
	v_mbcnt_hi_u32_b32 v0, s7, v0
	v_cmp_eq_u32_e32 vcc, 0, v0
	s_waitcnt vmcnt(0)
	buffer_inv sc1
	s_and_saveexec_b64 s[8:9], vcc
	s_cbranch_execz .LBB0_1580
	s_bcnt1_i32_b64 s2, s[6:7]

.LBB0_1675:
	s_or_b64 exec, exec, s[6:7]
	s_and_saveexec_b64 s[6:7], s[10:11]
	s_cbranch_execz .LBB0_1677
.LBB0_1677:
	s_or_b64 exec, exec, s[6:7]
	s_mov_b64 s[6:7], exec
	v_mbcnt_lo_u32_b32 v0, s6, 0
	v_mbcnt_hi_u32_b32 v0, s7, v0
	v_cmp_eq_u32_e32 vcc, 0, v0
	s_waitcnt vmcnt(0)
	buffer_inv sc1
	s_and_saveexec_b64 s[8:9], vcc
	s_cbranch_execz .LBB0_1679
	s_bcnt1_i32_b64 s2, s[6:7]

.LBB0_1738:
	s_or_b64 exec, exec, s[6:7]
	s_and_saveexec_b64 s[6:7], s[10:11]
	s_cbranch_execz .LBB0_1740
.LBB0_1740:
	s_or_b64 exec, exec, s[6:7]
	s_mov_b64 s[6:7], exec
	v_mbcnt_lo_u32_b32 v0, s6, 0
	v_mbcnt_hi_u32_b32 v0, s7, v0
	v_cmp_eq_u32_e32 vcc, 0, v0
	s_waitcnt vmcnt(0)
	buffer_inv sc1
	s_and_saveexec_b64 s[8:9], vcc
	s_cbranch_execz .LBB0_1742
	s_bcnt1_i32_b64 s2, s[6:7]

.LBB0_1793:
	s_or_b64 exec, exec, s[6:7]
	s_and_saveexec_b64 s[6:7], s[10:11]
	s_cbranch_execz .LBB0_1795
.LBB0_1795:
	s_or_b64 exec, exec, s[6:7]
	s_mov_b64 s[6:7], exec
	v_mbcnt_lo_u32_b32 v0, s6, 0
	v_mbcnt_hi_u32_b32 v0, s7, v0
	v_cmp_eq_u32_e32 vcc, 0, v0
	s_waitcnt vmcnt(0)
	buffer_inv sc1
	s_and_saveexec_b64 s[8:9], vcc
	s_cbranch_execz .LBB0_1797
	s_bcnt1_i32_b64 s2, s[6:7]

.LBB0_1856:
	s_or_b64 exec, exec, s[6:7]
	s_and_saveexec_b64 s[6:7], s[10:11]
	s_cbranch_execz .LBB0_1858
.LBB0_1858:
	s_or_b64 exec, exec, s[6:7]
	s_mov_b64 s[6:7], exec
	v_mbcnt_lo_u32_b32 v0, s6, 0
	v_mbcnt_hi_u32_b32 v0, s7, v0
	v_cmp_eq_u32_e32 vcc, 0, v0
	s_waitcnt vmcnt(0)
	buffer_inv sc1
	s_and_saveexec_b64 s[8:9], vcc
	s_cbranch_execz .LBB0_1860
	s_bcnt1_i32_b64 s2, s[6:7]

.LBB0_1919:
	s_or_b64 exec, exec, s[6:7]
	s_and_saveexec_b64 s[6:7], s[10:11]
	s_cbranch_execz .LBB0_1921
.LBB0_1921:
	s_or_b64 exec, exec, s[6:7]
	s_mov_b64 s[6:7], exec
	v_mbcnt_lo_u32_b32 v0, s6, 0
	v_mbcnt_hi_u32_b32 v0, s7, v0
	v_cmp_eq_u32_e32 vcc, 0, v0
	s_waitcnt vmcnt(0)
	buffer_inv sc1
	s_and_saveexec_b64 s[8:9], vcc
	s_cbranch_execz .LBB0_1923
	s_bcnt1_i32_b64 s2, s[6:7]
